# streaming hint extended: the final rmsnorm's last read of the residual stream also uses non-temporal loads
# baseline (speedup 1.0000x reference)
; DI void rmsnorm_phase(const float* __restrict__ X, const float* __restrict__ g, bf16_t* __restrict__ H, float* __restrict__ OF) {
;     ...
;   for (int row = gw; row < T; row += nw) {
;     const float* xr = X + (size_t)row * D;
;     f32x4 v[8];
;     float ss = 0.f;
; #pragma unroll
;     for (int i = 0; i < 8; ++i) { v[i] = *(const f32x4*)(xr + lane * 4 + 256 * i); ss += v[i][0] * v[i][0] + v[i][1] * v[i][1] + v[i][2] * v[i][2] + v[i][3] * v[i][3]; }
;     ss = wave_sum(ss);
;     const float rstd = rsqrtf(ss * (1.f / D) + EPS);
; #pragma unroll
;     for (int i = 0; i < 8; ++i) {
;       const f32x4 gg = *(const f32x4*)(g + lane * 4 + 256 * i);
;       f32x4 o = v[i] * rstd * gg;
;       if (H) { u32x2 w; w.x = pk_bf16(o[0], o[1]); w.y = pk_bf16(o[2], o[3]); *(u32x2*)(H + (size_t)row * D + lane * 4 + 256 * i) = w; }
;       else *(f32x4*)(OF + (size_t)row * D + lane * 4 + 256 * i) = o;
;     }
;   }
.LBB0_1709:
	global_load_dwordx4 v[42:45], v[34:35], off offset:-4096 nt
	global_load_dwordx4 v[46:49], v[34:35], off offset:-3072 nt
	global_load_dwordx4 v[50:53], v[34:35], off offset:-2048 nt
	global_load_dwordx4 v[54:57], v[34:35], off offset:-1024 nt
	global_load_dwordx4 v[58:61], v[34:35], off nt
	global_load_dwordx4 v[62:65], v[34:35], off offset:1024 nt
	global_load_dwordx4 v[66:69], v[34:35], off offset:2048 nt
	global_load_dwordx4 v[70:73], v[34:35], off offset:3072 nt
	v_add_u32_e32 v32, s26, v32
	v_cmp_lt_i32_e64 s[0:1], s7, v32
	s_or_b64 s[4:5], s[0:1], s[4:5]
	s_waitcnt vmcnt(7)
	v_mul_f32_e32 v90, v43, v43
	s_waitcnt vmcnt(6)
	v_mul_f32_e32 v91, v47, v47
	s_waitcnt vmcnt(5)
	v_mul_f32_e32 v92, v51, v51
	v_fmac_f32_e32 v90, v42, v42
	s_waitcnt vmcnt(3)
	v_mov_b32_e32 v76, v59
	s_waitcnt vmcnt(2)
	v_mov_b32_e32 v77, v63
	v_fmac_f32_e32 v91, v46, v46
	v_mul_f32_e32 v93, v55, v55
	v_mov_b32_e32 v74, v58
	v_mov_b32_e32 v75, v62
	v_fmac_f32_e32 v92, v50, v50
	v_pk_mul_f32 v[76:77], v[76:77], v[76:77]
	v_fmac_f32_e32 v90, v44, v44
	v_fmac_f32_e32 v91, v48, v48
	v_mov_b32_e32 v78, v60
	v_mov_b32_e32 v79, v64
	v_fmac_f32_e32 v93, v54, v54
	v_fmac_f32_e32 v92, v52, v52
	v_pk_fma_f32 v[74:75], v[74:75], v[74:75], v[76:77]
	v_fmac_f32_e32 v90, v45, v45
	v_fmac_f32_e32 v91, v49, v49
	s_waitcnt vmcnt(1)
	v_mov_b32_e32 v84, v67
	s_waitcnt vmcnt(0)
	v_mov_b32_e32 v85, v71
	v_fmac_f32_e32 v93, v56, v56
	v_fmac_f32_e32 v92, v53, v53
	v_pk_fma_f32 v[74:75], v[78:79], v[78:79], v[74:75]
	v_add_f32_e32 v78, v90, v91
	v_mov_b32_e32 v80, v61
	v_mov_b32_e32 v81, v65
	v_mov_b32_e32 v82, v66
	v_mov_b32_e32 v83, v70
	v_pk_mul_f32 v[84:85], v[84:85], v[84:85]
	v_fmac_f32_e32 v93, v57, v57
	v_add_f32_e32 v78, v78, v92
	v_mov_b32_e32 v86, v68
	v_mov_b32_e32 v87, v72
	v_pk_fma_f32 v[76:77], v[82:83], v[82:83], v[84:85]
	v_pk_fma_f32 v[74:75], v[80:81], v[80:81], v[74:75]
	v_add_f32_e32 v78, v78, v93
	v_mov_b32_e32 v88, v69
	v_mov_b32_e32 v89, v73
	v_pk_fma_f32 v[76:77], v[86:87], v[86:87], v[76:77]
	v_add_f32_e32 v74, v78, v74
	v_pk_fma_f32 v[76:77], v[88:89], v[88:89], v[76:77]
	v_add_f32_e32 v74, v74, v75
	v_add_f32_e32 v74, v74, v76
	v_add_f32_e32 v74, v74, v77
	ds_bpermute_b32 v75, v36, v74
	s_waitcnt lgkmcnt(0)
	v_add_f32_e32 v74, v74, v75
	ds_bpermute_b32 v75, v37, v74
	s_waitcnt lgkmcnt(0)
	v_add_f32_e32 v74, v74, v75
	ds_bpermute_b32 v75, v38, v74
	s_waitcnt lgkmcnt(0)
	v_add_f32_e32 v74, v74, v75
	ds_bpermute_b32 v75, v39, v74
	s_waitcnt lgkmcnt(0)
	v_add_f32_e32 v74, v74, v75
	ds_bpermute_b32 v75, v40, v74
	s_waitcnt lgkmcnt(0)
	v_add_f32_e32 v74, v74, v75
	ds_bpermute_b32 v75, v41, v74
	s_waitcnt lgkmcnt(0)
	v_add_f32_e32 v74, v74, v75
	v_fmamk_f32 v74, v74, 0x3a000000, v33
	v_mul_f32_e32 v75, 0x4b800000, v74
	v_cmp_gt_f32_e32 vcc, s6, v74
	s_nop 1
	v_cndmask_b32_e32 v74, v74, v75, vcc
	v_rsq_f32_e32 v74, v74
	s_nop 0
	v_mul_f32_e32 v75, 0x45800000, v74
	v_cndmask_b32_e32 v74, v74, v75, vcc
	v_pk_mul_f32 v[42:43], v[42:43], v[74:75] op_sel_hi:[1,0]
	v_pk_mul_f32 v[44:45], v[44:45], v[74:75] op_sel_hi:[1,0]
	v_pk_mul_f32 v[46:47], v[46:47], v[74:75] op_sel_hi:[1,0]
	v_pk_mul_f32 v[48:49], v[48:49], v[74:75] op_sel_hi:[1,0]
	v_pk_mul_f32 v[50:51], v[50:51], v[74:75] op_sel_hi:[1,0]
	v_pk_mul_f32 v[52:53], v[52:53], v[74:75] op_sel_hi:[1,0]
	v_pk_mul_f32 v[54:55], v[54:55], v[74:75] op_sel_hi:[1,0]
	v_pk_mul_f32 v[56:57], v[56:57], v[74:75] op_sel_hi:[1,0]
	v_pk_mul_f32 v[58:59], v[58:59], v[74:75] op_sel_hi:[1,0]
	v_pk_mul_f32 v[60:61], v[60:61], v[74:75] op_sel_hi:[1,0]
	v_pk_mul_f32 v[62:63], v[62:63], v[74:75] op_sel_hi:[1,0]
	v_pk_mul_f32 v[64:65], v[64:65], v[74:75] op_sel_hi:[1,0]
	v_pk_mul_f32 v[66:67], v[66:67], v[74:75] op_sel_hi:[1,0]
	v_pk_mul_f32 v[68:69], v[68:69], v[74:75] op_sel_hi:[1,0]
	v_pk_mul_f32 v[70:71], v[70:71], v[74:75] op_sel_hi:[1,0]
	v_pk_mul_f32 v[72:73], v[72:73], v[74:75] op_sel_hi:[1,0]
	v_pk_mul_f32 v[44:45], v[2:3], v[44:45]
	v_pk_mul_f32 v[42:43], v[0:1], v[42:43]
	v_pk_mul_f32 v[48:49], v[6:7], v[48:49]
	v_pk_mul_f32 v[46:47], v[4:5], v[46:47]
	v_pk_mul_f32 v[52:53], v[10:11], v[52:53]
	v_pk_mul_f32 v[50:51], v[8:9], v[50:51]
	v_pk_mul_f32 v[56:57], v[14:15], v[56:57]
	v_pk_mul_f32 v[54:55], v[12:13], v[54:55]
	v_pk_mul_f32 v[60:61], v[18:19], v[60:61]
	v_pk_mul_f32 v[58:59], v[16:17], v[58:59]
	v_pk_mul_f32 v[64:65], v[22:23], v[64:65]
	v_pk_mul_f32 v[62:63], v[20:21], v[62:63]
	v_pk_mul_f32 v[68:69], v[26:27], v[68:69]
	v_pk_mul_f32 v[66:67], v[24:25], v[66:67]
	v_pk_mul_f32 v[72:73], v[30:31], v[72:73]
	v_pk_mul_f32 v[70:71], v[28:29], v[70:71]
	global_store_dwordx4 v[34:35], v[42:45], off offset:-4096
	global_store_dwordx4 v[34:35], v[46:49], off offset:-3072
	global_store_dwordx4 v[34:35], v[50:53], off offset:-2048
	global_store_dwordx4 v[34:35], v[54:57], off offset:-1024
	global_store_dwordx4 v[34:35], v[58:61], off
	global_store_dwordx4 v[34:35], v[62:65], off offset:1024
	global_store_dwordx4 v[34:35], v[66:69], off offset:2048
	global_store_dwordx4 v[34:35], v[70:73], off offset:3072
	v_lshl_add_u64 v[34:35], v[34:35], 0, s[2:3]
	s_andn2_b64 exec, exec, s[4:5]
	s_cbranch_execnz .LBB0_1709
